# GU polish: peeled first K-iteration with SrcC=0 (no accumulator zeroing), packed v_pk_mul/v_pk_add in the silu epilogue
# speedup vs baseline: 1.0035x; 1.0035x over previous
; #define LAS __attribute__((address_space(3)))
; #define BAR() { __builtin_amdgcn_sched_barrier(0); __builtin_amdgcn_s_barrier(); asm volatile("" ::: "memory"); __builtin_amdgcn_sched_barrier(0); }
; DI void gemm_stream2(const bf16_t* __restrict__ A, int lda, const bf16_t* __restrict__ Bt, int ldb, int K, int m0, int n0, ...
;     ...
;     for (int kt = 0; kt < nk; ++kt) {
;         const bool pf = (kt + 2 < nk) || has_next, more = (kt + 1 < nk) || has_next;
;         const bf16_t* pa = (kt + 2 < nk) ? ga + (kt + 2) * 64 : gan + (kt + 2 - nk) * 64;
;         const bf16_t* pb = (kt + 2 < nk) ? gb + (kt + 2) * 64 : gbn + (kt + 2 - nk) * 64;
;         const int plda = (kt + 2 < nk) ? lda : ldan, pldb = (kt + 2 < nk) ? ldb : ldbn;
;         const int s2 = st >= 1 ? st - 1 : 2;
;         const LAS char* base = lds + st * 49152;
; #pragma unroll
;         for (int ks = 0; ks < 2; ++ks) {
;             const unsigned fo = ks ? fo1 : fo0;
;             bf16x8 af[4], bfr[4];
; #pragma unroll
;             for (int i = 0; i < 4; ++i) { af[i] = *(const LAS bf16x8*)(base + aoff + i * 2048 + fo); bfr[i] = *(const LAS bf16x8*)(base + boff + i * 2048 + fo); }
;             if (ks == 1 && more) { if (pf) asm volatile("s_waitcnt vmcnt(3)" ::: "memory"); else asm volatile("s_waitcnt vmcnt(0)" ::: "memory"); }
;             if (pf) { PIECE(s2, ks * 3 + 0); PIECE(s2, ks * 3 + 1); PIECE(s2, ks * 3 + 2); }
;             asm volatile("s_waitcnt lgkmcnt(0)" ::: "memory");
;             BAR();
;             __builtin_amdgcn_s_setprio(1);
; #pragma unroll
;             for (int mi = 0; mi < 4; ++mi)
; #pragma unroll
;                 for (int ni = 0; ni < 4; ++ni) acc[mi][ni] = __builtin_amdgcn_mfma_f32_16x16x32_bf16(bfr[ni], af[mi], acc[mi][ni], 0, 0, 0);
;             __builtin_amdgcn_s_setprio(0);
;             BAR();
;         }
;         st = st == 2 ? 0 : st + 1;
;     }
; DI void zero_acc(f32x4 (&acc)[4][4]) {
; #pragma unroll
;     for (int i = 0; i < 4; ++i)
; #pragma unroll
;         for (int j = 0; j < 4; ++j) acc[i][j] = (f32x4){0.f, 0.f, 0.f, 0.f};
.Lgu_nonext:
	s_add_u32 s0, s54, 7
	ds_read_b128 v[0:3], v188 offset:16
	ds_read_b128 v[4:7], v189 offset:16
	ds_read_b128 v[8:11], v188 offset:2064
	ds_read_b128 v[12:15], v189 offset:2064
	ds_read_b128 v[152:155], v186 offset:16
	ds_read_b128 v[156:159], v187 offset:16
	ds_read_b128 v[160:163], v186 offset:2064
	ds_read_b128 v[164:167], v187 offset:2064
	ds_read_b128 v[168:171], v186 offset:4112
	ds_read_b128 v[172:175], v187 offset:4112
	ds_read_b128 v[176:179], v186 offset:6160
	ds_read_b128 v[180:183], v187 offset:6160
	s_add_i32 m0, s39, 0xc000
	s_nop 0
	global_load_lds_dwordx4 v184, s[68:69]
	s_add_i32 m0, s39, 0xc400
	s_nop 0
	global_load_lds_dwordx4 v185, s[68:69]
	s_add_u32 s68, s68, 0x80
	s_addc_u32 s69, s69, 0
	s_cmp_lg_u32 s0, s54
	s_cbranch_scc1 .Lgu_nosw1
	s_mov_b64 s[66:67], s[74:75]
	s_mov_b64 s[68:69], s[78:79]
	s_mov_b64 s[70:71], s[80:81]
	s_mov_b64 s[72:73], s[82:83]
.Lgu_nosw1:
	s_waitcnt lgkmcnt(8)
	s_barrier
	s_waitcnt lgkmcnt(0)
	s_setprio 1
	v_mfma_f32_16x16x32_bf16 v[24:27], v[0:3], v[152:155], 0
	v_mfma_f32_16x16x32_bf16 v[28:31], v[8:11], v[152:155], 0
	v_mfma_f32_16x16x32_bf16 v[32:35], v[0:3], v[160:163], 0
	v_mfma_f32_16x16x32_bf16 v[36:39], v[8:11], v[160:163], 0
	v_mfma_f32_16x16x32_bf16 v[40:43], v[0:3], v[168:171], 0
	v_mfma_f32_16x16x32_bf16 v[44:47], v[8:11], v[168:171], 0
	v_mfma_f32_16x16x32_bf16 v[48:51], v[0:3], v[176:179], 0
	v_mfma_f32_16x16x32_bf16 v[52:55], v[8:11], v[176:179], 0
	v_mfma_f32_16x16x32_bf16 v[24:27], v[4:7], v[156:159], v[24:27]
	v_mfma_f32_16x16x32_bf16 v[28:31], v[12:15], v[156:159], v[28:31]
	v_mfma_f32_16x16x32_bf16 v[32:35], v[4:7], v[164:167], v[32:35]
	v_mfma_f32_16x16x32_bf16 v[36:39], v[12:15], v[164:167], v[36:39]
	v_mfma_f32_16x16x32_bf16 v[40:43], v[4:7], v[172:175], v[40:43]
	v_mfma_f32_16x16x32_bf16 v[44:47], v[12:15], v[172:175], v[44:47]
	v_mfma_f32_16x16x32_bf16 v[48:51], v[4:7], v[180:183], v[48:51]
	v_mfma_f32_16x16x32_bf16 v[52:55], v[12:15], v[180:183], v[52:55]
	s_setprio 0
	s_barrier
	ds_read_b128 v[196:199], v188 offset:16400
	ds_read_b128 v[200:203], v189 offset:16400
	ds_read_b128 v[204:207], v188 offset:18448
	ds_read_b128 v[208:211], v189 offset:18448
	s_add_i32 m0, s39, 0x10000
	s_nop 0
	global_load_lds_dwordx4 v184, s[70:71]
	s_add_i32 m0, s39, 0x10400
	s_nop 0
	global_load_lds_dwordx4 v185, s[70:71]
	s_add_u32 s70, s70, 0x80
	s_addc_u32 s71, s71, 0
	s_barrier
	s_waitcnt lgkmcnt(0)
	s_setprio 1
	v_mfma_f32_16x16x32_bf16 v[56:59], v[196:199], v[152:155], 0
	v_mfma_f32_16x16x32_bf16 v[60:63], v[204:207], v[152:155], 0
	v_mfma_f32_16x16x32_bf16 v[64:67], v[196:199], v[160:163], 0
	v_mfma_f32_16x16x32_bf16 v[68:71], v[204:207], v[160:163], 0
	v_mfma_f32_16x16x32_bf16 v[72:75], v[196:199], v[168:171], 0
	v_mfma_f32_16x16x32_bf16 v[76:79], v[204:207], v[168:171], 0
	v_mfma_f32_16x16x32_bf16 v[80:83], v[196:199], v[176:179], 0
	v_mfma_f32_16x16x32_bf16 v[84:87], v[204:207], v[176:179], 0
	v_mfma_f32_16x16x32_bf16 v[56:59], v[200:203], v[156:159], v[56:59]
	v_mfma_f32_16x16x32_bf16 v[60:63], v[208:211], v[156:159], v[60:63]
	v_mfma_f32_16x16x32_bf16 v[64:67], v[200:203], v[164:167], v[64:67]
	v_mfma_f32_16x16x32_bf16 v[68:71], v[208:211], v[164:167], v[68:71]
	v_mfma_f32_16x16x32_bf16 v[72:75], v[200:203], v[172:175], v[72:75]
	v_mfma_f32_16x16x32_bf16 v[76:79], v[208:211], v[172:175], v[76:79]
	v_mfma_f32_16x16x32_bf16 v[80:83], v[200:203], v[180:183], v[80:83]
	v_mfma_f32_16x16x32_bf16 v[84:87], v[208:211], v[180:183], v[84:87]
	s_setprio 0
	s_barrier
	ds_read_b128 v[152:155], v186 offset:16400
	ds_read_b128 v[156:159], v187 offset:16400
	ds_read_b128 v[160:163], v186 offset:18448
	ds_read_b128 v[164:167], v187 offset:18448
	ds_read_b128 v[168:171], v186 offset:20496
	ds_read_b128 v[172:175], v187 offset:20496
	ds_read_b128 v[176:179], v186 offset:22544
	ds_read_b128 v[180:183], v187 offset:22544
	s_add_i32 m0, s39, 0x0
	s_nop 0
	global_load_lds_dwordx4 v184, s[66:67]
	s_add_i32 m0, s39, 0x400
	s_nop 0
	global_load_lds_dwordx4 v185, s[66:67]
	s_add_u32 s66, s66, 0x80
	s_addc_u32 s67, s67, 0
	s_barrier
	s_waitcnt lgkmcnt(0)
	s_setprio 1
	v_mfma_f32_16x16x32_bf16 v[88:91], v[0:3], v[152:155], 0
	v_mfma_f32_16x16x32_bf16 v[92:95], v[8:11], v[152:155], 0
	v_mfma_f32_16x16x32_bf16 v[96:99], v[0:3], v[160:163], 0
	v_mfma_f32_16x16x32_bf16 v[100:103], v[8:11], v[160:163], 0
	v_mfma_f32_16x16x32_bf16 v[104:107], v[0:3], v[168:171], 0
	v_mfma_f32_16x16x32_bf16 v[108:111], v[8:11], v[168:171], 0
	v_mfma_f32_16x16x32_bf16 v[112:115], v[0:3], v[176:179], 0
	v_mfma_f32_16x16x32_bf16 v[116:119], v[8:11], v[176:179], 0
	v_mfma_f32_16x16x32_bf16 v[88:91], v[4:7], v[156:159], v[88:91]
	v_mfma_f32_16x16x32_bf16 v[92:95], v[12:15], v[156:159], v[92:95]
	v_mfma_f32_16x16x32_bf16 v[96:99], v[4:7], v[164:167], v[96:99]
	v_mfma_f32_16x16x32_bf16 v[100:103], v[12:15], v[164:167], v[100:103]
	v_mfma_f32_16x16x32_bf16 v[104:107], v[4:7], v[172:175], v[104:107]
	v_mfma_f32_16x16x32_bf16 v[108:111], v[12:15], v[172:175], v[108:111]
	v_mfma_f32_16x16x32_bf16 v[112:115], v[4:7], v[180:183], v[112:115]
	v_mfma_f32_16x16x32_bf16 v[116:119], v[12:15], v[180:183], v[116:119]
	s_setprio 0
	s_barrier
	s_add_i32 m0, s39, 0x14000
	s_nop 0
	global_load_lds_dwordx4 v184, s[72:73]
	s_add_i32 m0, s39, 0x14400
	s_nop 0
	global_load_lds_dwordx4 v185, s[72:73]
	s_add_u32 s72, s72, 0x80
	s_addc_u32 s73, s73, 0
	s_waitcnt vmcnt(6)
	s_barrier
; #define LAS __attribute__((address_space(3)))
; #define BAR() { __builtin_amdgcn_sched_barrier(0); __builtin_amdgcn_s_barrier(); asm volatile("" ::: "memory"); __builtin_amdgcn_sched_barrier(0); }
; DI void gemm_stream2(const bf16_t* __restrict__ A, int lda, const bf16_t* __restrict__ Bt, int ldb, int K, int m0, int n0, ...
;     ...
;         for (int ks = 0; ks < 2; ++ks) {
;             const unsigned fo = ks ? fo1 : fo0;
;             bf16x8 af[4], bfr[4];
; #pragma unroll
;             for (int i = 0; i < 4; ++i) { af[i] = *(const LAS bf16x8*)(base + aoff + i * 2048 + fo); bfr[i] = *(const LAS bf16x8*)(base + boff + i * 2048 + fo); }
;             if (ks == 1 && more) { if (pf) asm volatile("s_waitcnt vmcnt(3)" ::: "memory"); else asm volatile("s_waitcnt vmcnt(0)" ::: "memory"); }
;             if (pf) { PIECE(s2, ks * 3 + 0); PIECE(s2, ks * 3 + 1); PIECE(s2, ks * 3 + 2); }
;             asm volatile("s_waitcnt lgkmcnt(0)" ::: "memory");
;             BAR();
;             __builtin_amdgcn_s_setprio(1);
; #pragma unroll
;             for (int mi = 0; mi < 4; ++mi)
; #pragma unroll
;                 for (int ni = 0; ni < 4; ++ni) acc[mi][ni] = __builtin_amdgcn_mfma_f32_16x16x32_bf16(bfr[ni], af[mi], acc[mi][ni], 0, 0, 0);
;             __builtin_amdgcn_s_setprio(0);
;             BAR();
;         }
	s_setprio 1
	v_mfma_f32_16x16x32_bf16 v[120:123], v[196:199], v[152:155], 0
	v_mfma_f32_16x16x32_bf16 v[124:127], v[204:207], v[152:155], 0
	v_mfma_f32_16x16x32_bf16 v[128:131], v[196:199], v[160:163], 0
	v_mfma_f32_16x16x32_bf16 v[132:135], v[204:207], v[160:163], 0
	v_mfma_f32_16x16x32_bf16 v[136:139], v[196:199], v[168:171], 0
	v_mfma_f32_16x16x32_bf16 v[140:143], v[204:207], v[168:171], 0
	v_mfma_f32_16x16x32_bf16 v[144:147], v[196:199], v[176:179], 0
	v_mfma_f32_16x16x32_bf16 v[148:151], v[204:207], v[176:179], 0
	v_mfma_f32_16x16x32_bf16 v[120:123], v[200:203], v[156:159], v[120:123]
	v_mfma_f32_16x16x32_bf16 v[124:127], v[208:211], v[156:159], v[124:127]
	v_mfma_f32_16x16x32_bf16 v[128:131], v[200:203], v[164:167], v[128:131]
	v_mfma_f32_16x16x32_bf16 v[132:135], v[208:211], v[164:167], v[132:135]
	v_mfma_f32_16x16x32_bf16 v[136:139], v[200:203], v[172:175], v[136:139]
	v_mfma_f32_16x16x32_bf16 v[140:143], v[208:211], v[172:175], v[140:143]
	v_mfma_f32_16x16x32_bf16 v[144:147], v[200:203], v[180:183], v[144:147]
	v_mfma_f32_16x16x32_bf16 v[148:151], v[208:211], v[180:183], v[148:151]
	s_setprio 0
	s_barrier
	ds_read_b128 v[0:3], v188 offset:32784
	ds_read_b128 v[4:7], v189 offset:32784
	ds_read_b128 v[8:11], v188 offset:34832
	ds_read_b128 v[12:15], v189 offset:34832
	ds_read_b128 v[152:155], v186 offset:32784
	ds_read_b128 v[156:159], v187 offset:32784
	ds_read_b128 v[160:163], v186 offset:34832
	ds_read_b128 v[164:167], v187 offset:34832
	ds_read_b128 v[168:171], v186 offset:36880
	ds_read_b128 v[172:175], v187 offset:36880
	ds_read_b128 v[176:179], v186 offset:38928
	ds_read_b128 v[180:183], v187 offset:38928
	s_add_i32 m0, s39, 0x4000
	s_nop 0
	global_load_lds_dwordx4 v184, s[68:69]
	s_add_i32 m0, s39, 0x4400
	s_nop 0
	global_load_lds_dwordx4 v185, s[68:69]
	s_add_u32 s68, s68, 0x80
	s_addc_u32 s69, s69, 0
	s_waitcnt lgkmcnt(8)
	s_barrier
	s_waitcnt lgkmcnt(0)
	s_setprio 1
	v_mfma_f32_16x16x32_bf16 v[24:27], v[0:3], v[152:155], v[24:27]
	v_mfma_f32_16x16x32_bf16 v[28:31], v[8:11], v[152:155], v[28:31]
	v_mfma_f32_16x16x32_bf16 v[32:35], v[0:3], v[160:163], v[32:35]
	v_mfma_f32_16x16x32_bf16 v[36:39], v[8:11], v[160:163], v[36:39]
	v_mfma_f32_16x16x32_bf16 v[40:43], v[0:3], v[168:171], v[40:43]
	v_mfma_f32_16x16x32_bf16 v[44:47], v[8:11], v[168:171], v[44:47]
	v_mfma_f32_16x16x32_bf16 v[48:51], v[0:3], v[176:179], v[48:51]
	v_mfma_f32_16x16x32_bf16 v[52:55], v[8:11], v[176:179], v[52:55]
	v_mfma_f32_16x16x32_bf16 v[24:27], v[4:7], v[156:159], v[24:27]
	v_mfma_f32_16x16x32_bf16 v[28:31], v[12:15], v[156:159], v[28:31]
	v_mfma_f32_16x16x32_bf16 v[32:35], v[4:7], v[164:167], v[32:35]
	v_mfma_f32_16x16x32_bf16 v[36:39], v[12:15], v[164:167], v[36:39]
	v_mfma_f32_16x16x32_bf16 v[40:43], v[4:7], v[172:175], v[40:43]
	v_mfma_f32_16x16x32_bf16 v[44:47], v[12:15], v[172:175], v[44:47]
	v_mfma_f32_16x16x32_bf16 v[48:51], v[4:7], v[180:183], v[48:51]
	v_mfma_f32_16x16x32_bf16 v[52:55], v[12:15], v[180:183], v[52:55]
	s_setprio 0
	s_barrier
	ds_read_b128 v[196:199], v188 offset:49168
	ds_read_b128 v[200:203], v189 offset:49168
	ds_read_b128 v[204:207], v188 offset:51216
	ds_read_b128 v[208:211], v189 offset:51216
	s_add_i32 m0, s39, 0x18000
	s_nop 0
	global_load_lds_dwordx4 v184, s[70:71]
	s_add_i32 m0, s39, 0x18400
	s_nop 0
	global_load_lds_dwordx4 v185, s[70:71]
	s_add_u32 s70, s70, 0x80
	s_addc_u32 s71, s71, 0
	s_barrier
; #define LAS __attribute__((address_space(3)))
; #define BAR() { __builtin_amdgcn_sched_barrier(0); __builtin_amdgcn_s_barrier(); asm volatile("" ::: "memory"); __builtin_amdgcn_sched_barrier(0); }
; DI void gemm_stream2(const bf16_t* __restrict__ A, int lda, const bf16_t* __restrict__ Bt, int ldb, int K, int m0, int n0, ...
;     ...
;     for (int kt = 0; kt < nk; ++kt) {
;         const bool pf = (kt + 2 < nk) || has_next, more = (kt + 1 < nk) || has_next;
;         const bf16_t* pa = (kt + 2 < nk) ? ga + (kt + 2) * 64 : gan + (kt + 2 - nk) * 64;
;         const bf16_t* pb = (kt + 2 < nk) ? gb + (kt + 2) * 64 : gbn + (kt + 2 - nk) * 64;
;         const int plda = (kt + 2 < nk) ? lda : ldan, pldb = (kt + 2 < nk) ? ldb : ldbn;
;         const int s2 = st >= 1 ? st - 1 : 2;
;         const LAS char* base = lds + st * 49152;
; #pragma unroll
;         for (int ks = 0; ks < 2; ++ks) {
;             const unsigned fo = ks ? fo1 : fo0;
;             bf16x8 af[4], bfr[4];
; #pragma unroll
;             for (int i = 0; i < 4; ++i) { af[i] = *(const LAS bf16x8*)(base + aoff + i * 2048 + fo); bfr[i] = *(const LAS bf16x8*)(base + boff + i * 2048 + fo); }
;             if (ks == 1 && more) { if (pf) asm volatile("s_waitcnt vmcnt(3)" ::: "memory"); else asm volatile("s_waitcnt vmcnt(0)" ::: "memory"); }
;             if (pf) { PIECE(s2, ks * 3 + 0); PIECE(s2, ks * 3 + 1); PIECE(s2, ks * 3 + 2); }
;             asm volatile("s_waitcnt lgkmcnt(0)" ::: "memory");
;             BAR();
;             __builtin_amdgcn_s_setprio(1);
; #pragma unroll
;             for (int mi = 0; mi < 4; ++mi)
; #pragma unroll
;                 for (int ni = 0; ni < 4; ++ni) acc[mi][ni] = __builtin_amdgcn_mfma_f32_16x16x32_bf16(bfr[ni], af[mi], acc[mi][ni], 0, 0, 0);
;             __builtin_amdgcn_s_setprio(0);
;             BAR();
;         }
;         st = st == 2 ? 0 : st + 1;
;     }
	s_waitcnt lgkmcnt(0)
	s_setprio 1
	v_mfma_f32_16x16x32_bf16 v[56:59], v[196:199], v[152:155], v[56:59]
	v_mfma_f32_16x16x32_bf16 v[60:63], v[204:207], v[152:155], v[60:63]
	v_mfma_f32_16x16x32_bf16 v[64:67], v[196:199], v[160:163], v[64:67]
	v_mfma_f32_16x16x32_bf16 v[68:71], v[204:207], v[160:163], v[68:71]
	v_mfma_f32_16x16x32_bf16 v[72:75], v[196:199], v[168:171], v[72:75]
	v_mfma_f32_16x16x32_bf16 v[76:79], v[204:207], v[168:171], v[76:79]
	v_mfma_f32_16x16x32_bf16 v[80:83], v[196:199], v[176:179], v[80:83]
	v_mfma_f32_16x16x32_bf16 v[84:87], v[204:207], v[176:179], v[84:87]
	v_mfma_f32_16x16x32_bf16 v[56:59], v[200:203], v[156:159], v[56:59]
	v_mfma_f32_16x16x32_bf16 v[60:63], v[208:211], v[156:159], v[60:63]
	v_mfma_f32_16x16x32_bf16 v[64:67], v[200:203], v[164:167], v[64:67]
	v_mfma_f32_16x16x32_bf16 v[68:71], v[208:211], v[164:167], v[68:71]
	v_mfma_f32_16x16x32_bf16 v[72:75], v[200:203], v[172:175], v[72:75]
	v_mfma_f32_16x16x32_bf16 v[76:79], v[208:211], v[172:175], v[76:79]
	v_mfma_f32_16x16x32_bf16 v[80:83], v[200:203], v[180:183], v[80:83]
	v_mfma_f32_16x16x32_bf16 v[84:87], v[208:211], v[180:183], v[84:87]
	s_setprio 0
	s_barrier
	ds_read_b128 v[152:155], v186 offset:49168
	ds_read_b128 v[156:159], v187 offset:49168
	ds_read_b128 v[160:163], v186 offset:51216
	ds_read_b128 v[164:167], v187 offset:51216
	ds_read_b128 v[168:171], v186 offset:53264
	ds_read_b128 v[172:175], v187 offset:53264
	ds_read_b128 v[176:179], v186 offset:55312
	ds_read_b128 v[180:183], v187 offset:55312
	s_add_i32 m0, s39, 0x8000
	s_nop 0
	global_load_lds_dwordx4 v184, s[66:67]
	s_add_i32 m0, s39, 0x8400
	s_nop 0
	global_load_lds_dwordx4 v185, s[66:67]
	s_add_u32 s66, s66, 0x80
	s_addc_u32 s67, s67, 0
	s_barrier
	s_waitcnt lgkmcnt(0)
	s_setprio 1
	v_mfma_f32_16x16x32_bf16 v[88:91], v[0:3], v[152:155], v[88:91]
	v_mfma_f32_16x16x32_bf16 v[92:95], v[8:11], v[152:155], v[92:95]
	v_mfma_f32_16x16x32_bf16 v[96:99], v[0:3], v[160:163], v[96:99]
	v_mfma_f32_16x16x32_bf16 v[100:103], v[8:11], v[160:163], v[100:103]
	v_mfma_f32_16x16x32_bf16 v[104:107], v[0:3], v[168:171], v[104:107]
	v_mfma_f32_16x16x32_bf16 v[108:111], v[8:11], v[168:171], v[108:111]
	v_mfma_f32_16x16x32_bf16 v[112:115], v[0:3], v[176:179], v[112:115]
	v_mfma_f32_16x16x32_bf16 v[116:119], v[8:11], v[176:179], v[116:119]
	v_mfma_f32_16x16x32_bf16 v[88:91], v[4:7], v[156:159], v[88:91]
	v_mfma_f32_16x16x32_bf16 v[92:95], v[12:15], v[156:159], v[92:95]
	v_mfma_f32_16x16x32_bf16 v[96:99], v[4:7], v[164:167], v[96:99]
	v_mfma_f32_16x16x32_bf16 v[100:103], v[12:15], v[164:167], v[100:103]
	v_mfma_f32_16x16x32_bf16 v[104:107], v[4:7], v[172:175], v[104:107]
	v_mfma_f32_16x16x32_bf16 v[108:111], v[12:15], v[172:175], v[108:111]
	v_mfma_f32_16x16x32_bf16 v[112:115], v[4:7], v[180:183], v[112:115]
	v_mfma_f32_16x16x32_bf16 v[116:119], v[12:15], v[180:183], v[116:119]
	s_setprio 0
	s_barrier
	s_add_i32 m0, s39, 0x1c000
	s_nop 0
	global_load_lds_dwordx4 v184, s[72:73]
	s_add_i32 m0, s39, 0x1c400
	s_nop 0
	global_load_lds_dwordx4 v185, s[72:73]
	s_add_u32 s72, s72, 0x80
	s_addc_u32 s73, s73, 0
	s_waitcnt vmcnt(6)
	s_barrier
	s_setprio 1
	v_mfma_f32_16x16x32_bf16 v[120:123], v[196:199], v[152:155], v[120:123]
	v_mfma_f32_16x16x32_bf16 v[124:127], v[204:207], v[152:155], v[124:127]
	v_mfma_f32_16x16x32_bf16 v[128:131], v[196:199], v[160:163], v[128:131]
	v_mfma_f32_16x16x32_bf16 v[132:135], v[204:207], v[160:163], v[132:135]
	v_mfma_f32_16x16x32_bf16 v[136:139], v[196:199], v[168:171], v[136:139]
	v_mfma_f32_16x16x32_bf16 v[140:143], v[204:207], v[168:171], v[140:143]
	v_mfma_f32_16x16x32_bf16 v[144:147], v[196:199], v[176:179], v[144:147]
	v_mfma_f32_16x16x32_bf16 v[148:151], v[204:207], v[176:179], v[148:151]
	v_mfma_f32_16x16x32_bf16 v[120:123], v[200:203], v[156:159], v[120:123]
	v_mfma_f32_16x16x32_bf16 v[124:127], v[208:211], v[156:159], v[124:127]
	v_mfma_f32_16x16x32_bf16 v[128:131], v[200:203], v[164:167], v[128:131]
	v_mfma_f32_16x16x32_bf16 v[132:135], v[208:211], v[164:167], v[132:135]
	v_mfma_f32_16x16x32_bf16 v[136:139], v[200:203], v[172:175], v[136:139]
	v_mfma_f32_16x16x32_bf16 v[140:143], v[208:211], v[172:175], v[140:143]
	v_mfma_f32_16x16x32_bf16 v[144:147], v[200:203], v[180:183], v[144:147]
	v_mfma_f32_16x16x32_bf16 v[148:151], v[208:211], v[180:183], v[148:151]
	s_setprio 0
	s_barrier
	s_sub_u32 s0, s0, 1

; DI unsigned pk2(float lo, float hi) { const f32x2 v = {lo, hi}; return __builtin_bit_cast(unsigned, __builtin_convertvector(v, bf2_t)); }
; DI void gemm_gu(const Params& p, size_t woff, int bid, int nb, char* smem, const int tid) {
;     ...
;         const int nb0 = n0 + wn * 64;
; #pragma unroll
;         for (int mi = 0; mi < 4; ++mi) {
;             const int row = m0 + wm * 64 + mi * 16 + r;
; #pragma unroll
;             for (int pr = 0; pr < 2; ++pr) {
;                 const f32x4 g = acc[mi][2 * pr], u = acc[mi][2 * pr + 1];
;                 float o[4];
; #pragma unroll
;                 for (int j = 0; j < 4; ++j) o[j] = g[j] * __builtin_amdgcn_rcpf(1.0f + __builtin_amdgcn_exp2f(-LOG2E * g[j])) * u[j];
;                 const int col = ((nb0 + pr * 32) >> 5) * 16 + q * 4;
;                 u32x2 w; w.x = pk2(o[0], o[1]); w.y = pk2(o[2], o[3]);
;                 *(u32x2*)(ACT + (size_t)row * DFF + col) = w;
;             }
;         }
.Lgu_epi:
	s_mul_i32 s1, s57, 0x160000
	s_lshl_b32 s62, s58, 8
	s_add_u32 s1, s1, s62
	s_add_u32 s1, s1, 0x52c0000
	s_add_u32 s2, s88, s1
	s_addc_u32 s3, s89, 0
	s_mov_b32 s96, 0xbfb8aa3b
	s_mov_b32 s97, 0xbfb8aa3b
	s_mov_b32 s98, 1.0
	s_mov_b32 s99, 1.0
	s_nop 7
	s_nop 7
	v_pk_mul_f32 v[152:153], v[24:25], s[96:97]
	v_pk_mul_f32 v[154:155], v[26:27], s[96:97]
	v_exp_f32_e32 v152, v152
	v_exp_f32_e32 v153, v153
	v_exp_f32_e32 v154, v154
	v_exp_f32_e32 v155, v155
	s_nop 0
	v_pk_add_f32 v[152:153], v[152:153], s[98:99]
	v_pk_add_f32 v[154:155], v[154:155], s[98:99]
	v_rcp_f32_e32 v152, v152
	v_rcp_f32_e32 v153, v153
	v_rcp_f32_e32 v154, v154
	v_rcp_f32_e32 v155, v155
	s_nop 0
	v_pk_mul_f32 v[152:153], v[24:25], v[152:153]
	v_pk_mul_f32 v[154:155], v[26:27], v[154:155]
	v_pk_mul_f32 v[152:153], v[28:29], v[152:153]
	v_pk_mul_f32 v[154:155], v[30:31], v[154:155]
	v_cvt_pk_bf16_f32 v152, v152, v153
	v_cvt_pk_bf16_f32 v153, v154, v155
	global_store_dwordx2 v237, v[152:153], s[2:3] offset:0
	v_pk_mul_f32 v[156:157], v[56:57], s[96:97]
	v_pk_mul_f32 v[158:159], v[58:59], s[96:97]
	v_exp_f32_e32 v156, v156
	v_exp_f32_e32 v157, v157
	v_exp_f32_e32 v158, v158
	v_exp_f32_e32 v159, v159
	s_nop 0
	v_pk_add_f32 v[156:157], v[156:157], s[98:99]
	v_pk_add_f32 v[158:159], v[158:159], s[98:99]
	v_rcp_f32_e32 v156, v156
	v_rcp_f32_e32 v157, v157
	v_rcp_f32_e32 v158, v158
	v_rcp_f32_e32 v159, v159
	s_nop 0
	v_pk_mul_f32 v[156:157], v[56:57], v[156:157]
	v_pk_mul_f32 v[158:159], v[58:59], v[158:159]
	v_pk_mul_f32 v[156:157], v[60:61], v[156:157]
	v_pk_mul_f32 v[158:159], v[62:63], v[158:159]
	v_cvt_pk_bf16_f32 v156, v156, v157
	v_cvt_pk_bf16_f32 v157, v158, v159
	global_store_dwordx2 v237, v[156:157], s[2:3] offset:128
	s_add_u32 s2, s2, 0x16000
	s_addc_u32 s3, s3, 0
	v_pk_mul_f32 v[160:161], v[32:33], s[96:97]
	v_pk_mul_f32 v[162:163], v[34:35], s[96:97]
	v_exp_f32_e32 v160, v160
	v_exp_f32_e32 v161, v161
	v_exp_f32_e32 v162, v162
	v_exp_f32_e32 v163, v163
	s_nop 0
	v_pk_add_f32 v[160:161], v[160:161], s[98:99]
	v_pk_add_f32 v[162:163], v[162:163], s[98:99]
	v_rcp_f32_e32 v160, v160
	v_rcp_f32_e32 v161, v161
	v_rcp_f32_e32 v162, v162
	v_rcp_f32_e32 v163, v163
	s_nop 0
	v_pk_mul_f32 v[160:161], v[32:33], v[160:161]
	v_pk_mul_f32 v[162:163], v[34:35], v[162:163]
	v_pk_mul_f32 v[160:161], v[36:37], v[160:161]
	v_pk_mul_f32 v[162:163], v[38:39], v[162:163]
	v_cvt_pk_bf16_f32 v160, v160, v161
	v_cvt_pk_bf16_f32 v161, v162, v163
	global_store_dwordx2 v237, v[160:161], s[2:3] offset:0
	v_pk_mul_f32 v[164:165], v[64:65], s[96:97]
	v_pk_mul_f32 v[166:167], v[66:67], s[96:97]
	v_exp_f32_e32 v164, v164
	v_exp_f32_e32 v165, v165
	v_exp_f32_e32 v166, v166
	v_exp_f32_e32 v167, v167
	s_nop 0
	v_pk_add_f32 v[164:165], v[164:165], s[98:99]
	v_pk_add_f32 v[166:167], v[166:167], s[98:99]
	v_rcp_f32_e32 v164, v164
	v_rcp_f32_e32 v165, v165
	v_rcp_f32_e32 v166, v166
	v_rcp_f32_e32 v167, v167
	s_nop 0
	v_pk_mul_f32 v[164:165], v[64:65], v[164:165]
	v_pk_mul_f32 v[166:167], v[66:67], v[166:167]
	v_pk_mul_f32 v[164:165], v[68:69], v[164:165]
	v_pk_mul_f32 v[166:167], v[70:71], v[166:167]
	v_cvt_pk_bf16_f32 v164, v164, v165
	v_cvt_pk_bf16_f32 v165, v166, v167
	global_store_dwordx2 v237, v[164:165], s[2:3] offset:128
	s_add_u32 s2, s2, 0x16000
	s_addc_u32 s3, s3, 0
	v_pk_mul_f32 v[168:169], v[40:41], s[96:97]
	v_pk_mul_f32 v[170:171], v[42:43], s[96:97]
	v_exp_f32_e32 v168, v168
	v_exp_f32_e32 v169, v169
	v_exp_f32_e32 v170, v170
	v_exp_f32_e32 v171, v171
	s_nop 0
	v_pk_add_f32 v[168:169], v[168:169], s[98:99]
	v_pk_add_f32 v[170:171], v[170:171], s[98:99]
	v_rcp_f32_e32 v168, v168
	v_rcp_f32_e32 v169, v169
	v_rcp_f32_e32 v170, v170
	v_rcp_f32_e32 v171, v171
	s_nop 0
	v_pk_mul_f32 v[168:169], v[40:41], v[168:169]
	v_pk_mul_f32 v[170:171], v[42:43], v[170:171]
	v_pk_mul_f32 v[168:169], v[44:45], v[168:169]
	v_pk_mul_f32 v[170:171], v[46:47], v[170:171]
	v_cvt_pk_bf16_f32 v168, v168, v169
	v_cvt_pk_bf16_f32 v169, v170, v171
	global_store_dwordx2 v237, v[168:169], s[2:3] offset:0
	v_pk_mul_f32 v[172:173], v[72:73], s[96:97]
	v_pk_mul_f32 v[174:175], v[74:75], s[96:97]
	v_exp_f32_e32 v172, v172
	v_exp_f32_e32 v173, v173
	v_exp_f32_e32 v174, v174
	v_exp_f32_e32 v175, v175
	s_nop 0
	v_pk_add_f32 v[172:173], v[172:173], s[98:99]
	v_pk_add_f32 v[174:175], v[174:175], s[98:99]
	v_rcp_f32_e32 v172, v172
	v_rcp_f32_e32 v173, v173
	v_rcp_f32_e32 v174, v174
	v_rcp_f32_e32 v175, v175
	s_nop 0
	v_pk_mul_f32 v[172:173], v[72:73], v[172:173]
	v_pk_mul_f32 v[174:175], v[74:75], v[174:175]
	v_pk_mul_f32 v[172:173], v[76:77], v[172:173]
	v_pk_mul_f32 v[174:175], v[78:79], v[174:175]
	v_cvt_pk_bf16_f32 v172, v172, v173
	v_cvt_pk_bf16_f32 v173, v174, v175
	global_store_dwordx2 v237, v[172:173], s[2:3] offset:128
	s_add_u32 s2, s2, 0x16000
	s_addc_u32 s3, s3, 0
	v_pk_mul_f32 v[152:153], v[48:49], s[96:97]
	v_pk_mul_f32 v[154:155], v[50:51], s[96:97]
	v_exp_f32_e32 v152, v152
	v_exp_f32_e32 v153, v153
	v_exp_f32_e32 v154, v154
	v_exp_f32_e32 v155, v155
	s_nop 0
	v_pk_add_f32 v[152:153], v[152:153], s[98:99]
	v_pk_add_f32 v[154:155], v[154:155], s[98:99]
	v_rcp_f32_e32 v152, v152
	v_rcp_f32_e32 v153, v153
	v_rcp_f32_e32 v154, v154
	v_rcp_f32_e32 v155, v155
	s_nop 0
	v_pk_mul_f32 v[152:153], v[48:49], v[152:153]
	v_pk_mul_f32 v[154:155], v[50:51], v[154:155]
	v_pk_mul_f32 v[152:153], v[52:53], v[152:153]
	v_pk_mul_f32 v[154:155], v[54:55], v[154:155]
	v_cvt_pk_bf16_f32 v152, v152, v153
	v_cvt_pk_bf16_f32 v153, v154, v155
	global_store_dwordx2 v237, v[152:153], s[2:3] offset:0
	v_pk_mul_f32 v[156:157], v[80:81], s[96:97]
	v_pk_mul_f32 v[158:159], v[82:83], s[96:97]
	v_exp_f32_e32 v156, v156
	v_exp_f32_e32 v157, v157
; DI unsigned pk2(float lo, float hi) { const f32x2 v = {lo, hi}; return __builtin_bit_cast(unsigned, __builtin_convertvector(v, bf2_t)); }
; DI void gemm_gu(const Params& p, size_t woff, int bid, int nb, char* smem, const int tid) {
;     ...
;         const int nb0 = n0 + wn * 64;
; #pragma unroll
;         for (int mi = 0; mi < 4; ++mi) {
;             const int row = m0 + wm * 64 + mi * 16 + r;
; #pragma unroll
;             for (int pr = 0; pr < 2; ++pr) {
;                 const f32x4 g = acc[mi][2 * pr], u = acc[mi][2 * pr + 1];
;                 float o[4];
; #pragma unroll
;                 for (int j = 0; j < 4; ++j) o[j] = g[j] * __builtin_amdgcn_rcpf(1.0f + __builtin_amdgcn_exp2f(-LOG2E * g[j])) * u[j];
;                 const int col = ((nb0 + pr * 32) >> 5) * 16 + q * 4;
;                 u32x2 w; w.x = pk2(o[0], o[1]); w.y = pk2(o[2], o[3]);
;                 *(u32x2*)(ACT + (size_t)row * DFF + col) = w;
;             }
;         }
	v_exp_f32_e32 v158, v158
	v_exp_f32_e32 v159, v159
	s_nop 0
	v_pk_add_f32 v[156:157], v[156:157], s[98:99]
	v_pk_add_f32 v[158:159], v[158:159], s[98:99]
	v_rcp_f32_e32 v156, v156
	v_rcp_f32_e32 v157, v157
	v_rcp_f32_e32 v158, v158
	v_rcp_f32_e32 v159, v159
	s_nop 0
	v_pk_mul_f32 v[156:157], v[80:81], v[156:157]
	v_pk_mul_f32 v[158:159], v[82:83], v[158:159]
	v_pk_mul_f32 v[156:157], v[84:85], v[156:157]
	v_pk_mul_f32 v[158:159], v[86:87], v[158:159]
	v_cvt_pk_bf16_f32 v156, v156, v157
	v_cvt_pk_bf16_f32 v157, v158, v159
	global_store_dwordx2 v237, v[156:157], s[2:3] offset:128
	s_add_u32 s2, s2, 0x6e000
	s_addc_u32 s3, s3, 0
	v_pk_mul_f32 v[160:161], v[88:89], s[96:97]
	v_pk_mul_f32 v[162:163], v[90:91], s[96:97]
	v_exp_f32_e32 v160, v160
	v_exp_f32_e32 v161, v161
	v_exp_f32_e32 v162, v162
	v_exp_f32_e32 v163, v163
	s_nop 0
	v_pk_add_f32 v[160:161], v[160:161], s[98:99]
	v_pk_add_f32 v[162:163], v[162:163], s[98:99]
	v_rcp_f32_e32 v160, v160
	v_rcp_f32_e32 v161, v161
	v_rcp_f32_e32 v162, v162
	v_rcp_f32_e32 v163, v163
	s_nop 0
	v_pk_mul_f32 v[160:161], v[88:89], v[160:161]
	v_pk_mul_f32 v[162:163], v[90:91], v[162:163]
	v_pk_mul_f32 v[160:161], v[92:93], v[160:161]
	v_pk_mul_f32 v[162:163], v[94:95], v[162:163]
	v_cvt_pk_bf16_f32 v160, v160, v161
	v_cvt_pk_bf16_f32 v161, v162, v163
	global_store_dwordx2 v237, v[160:161], s[2:3] offset:0
	v_pk_mul_f32 v[164:165], v[120:121], s[96:97]
	v_pk_mul_f32 v[166:167], v[122:123], s[96:97]
	v_exp_f32_e32 v164, v164
	v_exp_f32_e32 v165, v165
	v_exp_f32_e32 v166, v166
	v_exp_f32_e32 v167, v167
	s_nop 0
	v_pk_add_f32 v[164:165], v[164:165], s[98:99]
	v_pk_add_f32 v[166:167], v[166:167], s[98:99]
	v_rcp_f32_e32 v164, v164
	v_rcp_f32_e32 v165, v165
	v_rcp_f32_e32 v166, v166
	v_rcp_f32_e32 v167, v167
	s_nop 0
	v_pk_mul_f32 v[164:165], v[120:121], v[164:165]
	v_pk_mul_f32 v[166:167], v[122:123], v[166:167]
	v_pk_mul_f32 v[164:165], v[124:125], v[164:165]
	v_pk_mul_f32 v[166:167], v[126:127], v[166:167]
	v_cvt_pk_bf16_f32 v164, v164, v165
	v_cvt_pk_bf16_f32 v165, v166, v167
	global_store_dwordx2 v237, v[164:165], s[2:3] offset:128
	s_add_u32 s2, s2, 0x16000
	s_addc_u32 s3, s3, 0
	v_pk_mul_f32 v[168:169], v[96:97], s[96:97]
	v_pk_mul_f32 v[170:171], v[98:99], s[96:97]
	v_exp_f32_e32 v168, v168
	v_exp_f32_e32 v169, v169
	v_exp_f32_e32 v170, v170
	v_exp_f32_e32 v171, v171
	s_nop 0
	v_pk_add_f32 v[168:169], v[168:169], s[98:99]
	v_pk_add_f32 v[170:171], v[170:171], s[98:99]
	v_rcp_f32_e32 v168, v168
	v_rcp_f32_e32 v169, v169
	v_rcp_f32_e32 v170, v170
	v_rcp_f32_e32 v171, v171
	s_nop 0
	v_pk_mul_f32 v[168:169], v[96:97], v[168:169]
	v_pk_mul_f32 v[170:171], v[98:99], v[170:171]
	v_pk_mul_f32 v[168:169], v[100:101], v[168:169]
	v_pk_mul_f32 v[170:171], v[102:103], v[170:171]
	v_cvt_pk_bf16_f32 v168, v168, v169
	v_cvt_pk_bf16_f32 v169, v170, v171
	global_store_dwordx2 v237, v[168:169], s[2:3] offset:0
	v_pk_mul_f32 v[172:173], v[128:129], s[96:97]
	v_pk_mul_f32 v[174:175], v[130:131], s[96:97]
	v_exp_f32_e32 v172, v172
	v_exp_f32_e32 v173, v173
	v_exp_f32_e32 v174, v174
	v_exp_f32_e32 v175, v175
	s_nop 0
	v_pk_add_f32 v[172:173], v[172:173], s[98:99]
	v_pk_add_f32 v[174:175], v[174:175], s[98:99]
	v_rcp_f32_e32 v172, v172
	v_rcp_f32_e32 v173, v173
	v_rcp_f32_e32 v174, v174
	v_rcp_f32_e32 v175, v175
	s_nop 0
	v_pk_mul_f32 v[172:173], v[128:129], v[172:173]
	v_pk_mul_f32 v[174:175], v[130:131], v[174:175]
	v_pk_mul_f32 v[172:173], v[132:133], v[172:173]
	v_pk_mul_f32 v[174:175], v[134:135], v[174:175]
	v_cvt_pk_bf16_f32 v172, v172, v173
	v_cvt_pk_bf16_f32 v173, v174, v175
	global_store_dwordx2 v237, v[172:173], s[2:3] offset:128
	s_add_u32 s2, s2, 0x16000
	s_addc_u32 s3, s3, 0
	v_pk_mul_f32 v[152:153], v[104:105], s[96:97]
	v_pk_mul_f32 v[154:155], v[106:107], s[96:97]
	v_exp_f32_e32 v152, v152
	v_exp_f32_e32 v153, v153
	v_exp_f32_e32 v154, v154
	v_exp_f32_e32 v155, v155
	s_nop 0
	v_pk_add_f32 v[152:153], v[152:153], s[98:99]
	v_pk_add_f32 v[154:155], v[154:155], s[98:99]
	v_rcp_f32_e32 v152, v152
	v_rcp_f32_e32 v153, v153
	v_rcp_f32_e32 v154, v154
	v_rcp_f32_e32 v155, v155
	s_nop 0
	v_pk_mul_f32 v[152:153], v[104:105], v[152:153]
	v_pk_mul_f32 v[154:155], v[106:107], v[154:155]
	v_pk_mul_f32 v[152:153], v[108:109], v[152:153]
	v_pk_mul_f32 v[154:155], v[110:111], v[154:155]
	v_cvt_pk_bf16_f32 v152, v152, v153
	v_cvt_pk_bf16_f32 v153, v154, v155
	global_store_dwordx2 v237, v[152:153], s[2:3] offset:0
	v_pk_mul_f32 v[156:157], v[136:137], s[96:97]
	v_pk_mul_f32 v[158:159], v[138:139], s[96:97]
	v_exp_f32_e32 v156, v156
	v_exp_f32_e32 v157, v157
	v_exp_f32_e32 v158, v158
	v_exp_f32_e32 v159, v159
	s_nop 0
	v_pk_add_f32 v[156:157], v[156:157], s[98:99]
	v_pk_add_f32 v[158:159], v[158:159], s[98:99]
	v_rcp_f32_e32 v156, v156
	v_rcp_f32_e32 v157, v157
	v_rcp_f32_e32 v158, v158
	v_rcp_f32_e32 v159, v159
	s_nop 0
	v_pk_mul_f32 v[156:157], v[136:137], v[156:157]
	v_pk_mul_f32 v[158:159], v[138:139], v[158:159]
	v_pk_mul_f32 v[156:157], v[140:141], v[156:157]
	v_pk_mul_f32 v[158:159], v[142:143], v[158:159]
	v_cvt_pk_bf16_f32 v156, v156, v157
	v_cvt_pk_bf16_f32 v157, v158, v159
	global_store_dwordx2 v237, v[156:157], s[2:3] offset:128
	s_add_u32 s2, s2, 0x16000
	s_addc_u32 s3, s3, 0
	v_pk_mul_f32 v[160:161], v[112:113], s[96:97]
	v_pk_mul_f32 v[162:163], v[114:115], s[96:97]
	v_exp_f32_e32 v160, v160
	v_exp_f32_e32 v161, v161
	v_exp_f32_e32 v162, v162
	v_exp_f32_e32 v163, v163
	s_nop 0
	v_pk_add_f32 v[160:161], v[160:161], s[98:99]
	v_pk_add_f32 v[162:163], v[162:163], s[98:99]
	v_rcp_f32_e32 v160, v160
	v_rcp_f32_e32 v161, v161
	v_rcp_f32_e32 v162, v162
	v_rcp_f32_e32 v163, v163
	s_nop 0
	v_pk_mul_f32 v[160:161], v[112:113], v[160:161]
	v_pk_mul_f32 v[162:163], v[114:115], v[162:163]
	v_pk_mul_f32 v[160:161], v[116:117], v[160:161]
	v_pk_mul_f32 v[162:163], v[118:119], v[162:163]
	v_cvt_pk_bf16_f32 v160, v160, v161
	v_cvt_pk_bf16_f32 v161, v162, v163
	global_store_dwordx2 v237, v[160:161], s[2:3] offset:0
	v_pk_mul_f32 v[164:165], v[144:145], s[96:97]
	v_pk_mul_f32 v[166:167], v[146:147], s[96:97]
	v_exp_f32_e32 v164, v164
	v_exp_f32_e32 v165, v165
	v_exp_f32_e32 v166, v166
	v_exp_f32_e32 v167, v167
	s_nop 0
	v_pk_add_f32 v[164:165], v[164:165], s[98:99]
	v_pk_add_f32 v[166:167], v[166:167], s[98:99]
	v_rcp_f32_e32 v164, v164
	v_rcp_f32_e32 v165, v165
	v_rcp_f32_e32 v166, v166
	v_rcp_f32_e32 v167, v167
	s_nop 0
	v_pk_mul_f32 v[164:165], v[144:145], v[164:165]
	v_pk_mul_f32 v[166:167], v[146:147], v[166:167]
	v_pk_mul_f32 v[164:165], v[148:149], v[164:165]
	v_pk_mul_f32 v[166:167], v[150:151], v[166:167]
	v_cvt_pk_bf16_f32 v164, v164, v165
	v_cvt_pk_bf16_f32 v165, v166, v167
	global_store_dwordx2 v237, v[164:165], s[2:3] offset:128
	s_cmp_eq_u32 s54, 0
	s_cbranch_scc1 .LBB0_860
	s_mov_b32 s51, s76
	s_mov_b32 s57, s59
	s_mov_b32 s58, s60
	s_branch .Lgu_tile
